# PC1 GEMM loop: read and stage only the B half this workgroup multiplies (bjsel), vmcnt recounted; no mid-segment lgkmcnt
# baseline (speedup 1.0000x reference)
.LBB0_1273:
	s_or_b64 exec, exec, s[14:15]
	s_mov_b64 s[4:5], s[96:97]
	s_waitcnt lgkmcnt(0)
	s_barrier
	s_load_dwordx2 s[26:27], s[4:5], 0x100
	v_readlane_b32 s4, v253, 27
	v_mov_b32_e32 v0, v244
	v_mov_b32_e32 v14, v244
	v_readlane_b32 s5, v253, 28
	s_waitcnt lgkmcnt(0)
	s_and_b64 vcc, exec, s[4:5]
	v_readfirstlane_b32 s20, v14
	s_cbranch_vccz .LBB0_1415
	v_lshlrev_b32_e32 v0, 4, v14
	v_add_u32_e32 v1, 0x2000, v0
	v_ashrrev_i32_e32 v2, 31, v1
	v_lshrrev_b32_e32 v2, 22, v2
	v_add_u32_e32 v2, v1, v2
	v_ashrrev_i32_e32 v8, 10, v2
	v_mul_i32_i24_e32 v2, 0x400, v8
	v_sub_u32_e32 v1, v1, v2
	v_lshrrev_b32_e32 v2, 4, v1
	v_readlane_b32 s4, v254, 45
	v_bitop3_b32 v1, v2, v1, 32 bitop3:0x6c
	v_readlane_b32 s5, v254, 46
	s_add_u32 s3, s26, 0x5800000
	v_ashrrev_i32_e32 v2, 31, v1
	s_mul_i32 s5, s4, 0x300000
	s_addc_u32 s4, s27, 0
	v_lshrrev_b32_e32 v2, 26, v2
	s_add_u32 s5, s26, s5
	v_add_u32_e32 v2, v1, v2
	v_lshlrev_b32_e32 v3, 3, v8
	s_addc_u32 s14, s27, 0
	v_ashrrev_i32_e32 v9, 6, v2
	v_and_b32_e32 v3, -16, v3
	s_add_u32 s5, s5, 0x1d00000
	v_add_u32_e32 v3, v9, v3
	s_addc_u32 s38, s14, 0
	v_and_b32_e32 v4, 3, v9
	s_mov_b32 s14, 0x3fffe0
	v_lshrrev_b32_e32 v5, 2, v3
	v_lshlrev_b32_e32 v6, 1, v3
	v_and_b32_e32 v2, 0xc0, v2
	v_and_or_b32 v4, v3, s14, v4
	v_and_b32_e32 v5, 4, v5
	v_and_b32_e32 v6, 24, v6
	v_sub_u32_e32 v1, v1, v2
	v_or3_b32 v4, v4, v5, v6
	v_lshlrev_b32_e32 v5, 5, v8
	v_ashrrev_i16_sdwa v1, v220, sext(v1) dst_sel:DWORD dst_unused:UNUSED_PAD src0_sel:DWORD src1_sel:BYTE_0
	v_and_b32_e32 v5, 32, v5
	v_bfe_i32 v10, v1, 0, 16
	v_add_lshl_u32 v1, v5, v10, 1
	v_lshl_add_u32 v194, v4, 10, v1
	v_lshl_add_u32 v196, v3, 10, v1
	v_bfe_i32 v1, v14, 27, 1
	v_lshrrev_b32_e32 v1, 22, v1
	v_add_u32_e32 v1, v0, v1
	v_and_b32_e32 v1, 0xfffffc00, v1
	v_sub_u32_e32 v0, v0, v1
	v_lshrrev_b32_e32 v1, 4, v0
	v_ashrrev_i32_e32 v2, 31, v14
	v_bitop3_b32 v0, v1, v0, 32 bitop3:0x6c
	v_lshrrev_b32_e32 v2, 26, v2
	v_ashrrev_i32_e32 v1, 31, v0
	v_add_u32_e32 v2, v14, v2
	v_lshrrev_b32_e32 v1, 26, v1
	v_ashrrev_i32_e32 v12, 6, v2
	v_add_u32_e32 v1, v0, v1
	v_lshlrev_b32_e32 v2, 3, v12
	v_ashrrev_i32_e32 v11, 6, v1
	v_and_b32_e32 v2, -16, v2
	v_add_u32_e32 v2, v11, v2
	s_ashr_i32 s22, s20, 6
	v_and_b32_e32 v3, 3, v11
	v_lshrrev_b32_e32 v4, 2, v2
	v_lshlrev_b32_e32 v5, 1, v2
	v_and_b32_e32 v1, 0xc0, v1
	s_ashr_i32 s21, s20, 8
	s_lshl_b32 s16, s22, 10
	v_and_or_b32 v3, v2, s14, v3
	v_and_b32_e32 v4, 4, v4
	v_and_b32_e32 v5, 24, v5
	v_sub_u32_e32 v0, v0, v1
	v_readlane_b32 s14, v253, 30
	v_or3_b32 v3, v3, v4, v5
	v_lshlrev_b32_e32 v4, 5, v12
	v_ashrrev_i16_sdwa v0, v220, sext(v0) dst_sel:DWORD dst_unused:UNUSED_PAD src0_sel:DWORD src1_sel:BYTE_0
	s_add_u32 s14, s5, s14
	v_and_b32_e32 v4, 32, v4
	v_bfe_i32 v13, v0, 0, 16
	s_addc_u32 s15, s38, 0
	s_add_i32 s39, s16, 0
	v_add_lshl_u32 v0, v4, v13, 1
	s_add_i32 s56, s39, 0x10000
	s_add_i32 s57, s39, 0x12000
	v_lshl_add_u32 v198, v3, 10, v0
	s_and_b64 vcc, exec, s[52:53]
	s_mov_b32 m0, s56
	s_add_u32 s16, s14, 0x20000
	s_cbranch_vccz .Lpc1_dsk_8
	global_load_lds_dwordx4 v198, s[14:15]
.Lpc1_dsk_8:
	s_mov_b32 m0, s57
	s_addc_u32 s17, s15, 0
	s_add_i32 s58, s39, 0x14000
	s_cbranch_vccz .Lpc1_dsk_9
	global_load_lds_dwordx4 v194, s[14:15]
.Lpc1_dsk_9:
	s_and_b64 vcc, exec, s[94:95]
	s_mov_b32 m0, s58
	s_add_i32 s59, s39, 0x16000
	s_cbranch_vccz .Lpc1_dsk_10
	global_load_lds_dwordx4 v198, s[16:17]
.Lpc1_dsk_10:
	s_mov_b32 m0, s59
	v_lshl_add_u32 v200, v2, 10, v0
	s_cbranch_vccz .Lpc1_dsk_11
	global_load_lds_dwordx4 v194, s[16:17]
.Lpc1_dsk_11:
	v_readlane_b32 s16, v253, 33
	v_readlane_b32 s17, v253, 34
	s_add_u32 s16, s3, s16
	s_addc_u32 s17, s4, s17
	s_add_i32 s60, s39, 0x2000
	s_mov_b32 m0, s39
	s_add_u32 s18, s16, 0x20000
	global_load_lds_dwordx4 v200, s[16:17]
	s_mov_b32 m0, s60
	s_addc_u32 s19, s17, 0
	s_add_i32 s61, s39, 0x4000
	global_load_lds_dwordx4 v196, s[16:17]
	s_mov_b32 m0, s61
	s_add_i32 s62, s39, 0x6000
	global_load_lds_dwordx4 v200, s[18:19]
	s_mov_b32 m0, s62
	v_mov_b32_e32 v199, v129
	global_load_lds_dwordx4 v196, s[18:19]
	v_mov_b32_e32 v195, v129
	v_mov_b32_e32 v201, v129
	v_mov_b32_e32 v197, v129
	s_cmp_eq_u32 s21, 1
	v_lshl_add_u64 v[6:7], s[14:15], 0, v[198:199]
	v_lshl_add_u64 v[4:5], s[14:15], 0, v[194:195]
	v_lshl_add_u64 v[0:1], s[16:17], 0, v[200:201]
	s_cselect_b64 s[18:19], -1, 0
	s_cmp_lg_u32 s21, 1
	v_lshl_add_u64 v[2:3], s[16:17], 0, v[196:197]
	s_cbranch_scc1 .LBB0_1276
	s_barrier
.LBB0_1276:
	v_bfe_u32 v215, v14, 4, 2
	v_and_b32_e32 v214, 15, v14
	v_lshlrev_b32_e32 v15, 4, v215
	v_lshlrev_b32_e32 v14, 2, v14
	s_add_i32 s65, s39, 0x18000
	s_and_b32 s22, s22, 3
	s_lshl_b32 s63, s21, 6
	v_lshl_or_b32 v15, v214, 6, v15
	s_lshl_b32 s21, s21, 13
	v_and_b32_e32 v14, 32, v14
	v_lshl_add_u64 v[6:7], v[6:7], 0, s[6:7]
	s_mov_b32 m0, s65
	s_add_i32 s66, s39, 0x1a000
	v_bitop3_b32 v16, v15, s21, v14 bitop3:0xde
	s_lshl_b32 s64, s22, 5
	s_lshl_b32 s21, s22, 12
	s_waitcnt vmcnt(2)
	s_barrier
	s_and_b64 vcc, exec, s[52:53]
	s_cbranch_vccz .Lpc1_dsk_12
	global_load_lds_dwordx4 v[6:7], off
.Lpc1_dsk_12:
	v_lshl_add_u64 v[4:5], v[4:5], 0, s[6:7]
	s_mov_b32 m0, s66
	s_add_i32 s68, s39, 0x8000
	s_add_i32 s70, s39, 0xa000
	s_cbranch_vccz .Lpc1_dsk_13
	global_load_lds_dwordx4 v[4:5], off
.Lpc1_dsk_13:
	v_lshl_add_u64 v[0:1], v[0:1], 0, s[6:7]
	s_mov_b32 m0, s68
	s_add_u32 s22, s14, 0x20080
	global_load_lds_dwordx4 v[0:1], off
	v_lshl_add_u64 v[0:1], v[2:3], 0, s[6:7]
	s_mov_b32 m0, s70
	s_addc_u32 s23, s15, 0
	s_and_b64 vcc, exec, s[94:95]
	s_add_i32 s71, s39, 0x1c000
	global_load_lds_dwordx4 v[0:1], off
	v_lshl_add_u64 v[0:1], s[22:23], 0, v[198:199]
	s_mov_b32 m0, s71
	s_add_i32 s72, s39, 0x1e000
	s_cbranch_vccz .Lpc1_dsk_14
	global_load_lds_dwordx4 v[0:1], off
.Lpc1_dsk_14:
	v_lshl_add_u64 v[0:1], s[22:23], 0, v[194:195]
	s_mov_b32 m0, s72
	s_cmpk_lt_u32 s20, 0x100
	s_cbranch_vccz .Lpc1_dsk_15
	global_load_lds_dwordx4 v[0:1], off
.Lpc1_dsk_15:
	v_lshlrev_b32_e32 v0, 13, v12
	v_and_b32_e32 v0, 0xffffc000, v0
	v_lshl_add_u32 v0, v11, 10, v0
	v_and_b32_e32 v1, 1, v12
	v_bitop3_b32 v14, v15, s21, v14 bitop3:0xde
	s_cselect_b64 s[20:21], -1, 0
	s_add_u32 s22, s26, 0x7000000
	v_lshl_or_b32 v0, v1, 6, v0
	s_addc_u32 s23, s27, 0
	v_lshl_add_u32 v202, v13, 1, v0
	v_lshlrev_b32_e32 v0, 13, v8
	s_add_u32 s24, s26, 0x9c00000
	v_and_b32_e32 v0, 0xffffc000, v0
	s_waitcnt vmcnt(4)
	s_addc_u32 s25, s27, 0
	v_lshl_add_u32 v0, v9, 10, v0
	v_and_b32_e32 v1, 1, v8
	s_add_u32 s26, s26, 0x4800000
	v_lshl_or_b32 v0, v1, 6, v0
	s_addc_u32 s27, s27, 0
	v_mov_b32_e32 v203, v129
	v_lshl_add_u32 v204, v10, 1, v0
	v_mov_b32_e32 v205, v129
	s_mov_b32 s73, 0
	v_add_u32_e32 v216, 0, v14
	v_add_u32_e32 v217, 0, v16
	v_readlane_b32 s28, v253, 29
	v_readlane_b32 s40, v253, 31
	s_barrier
	v_readlane_b32 s41, v253, 32
	s_branch .LBB0_1279

.LBB0_1281:
	s_and_b64 vcc, exec, s[52:53]
	s_cbranch_vccz .Lpc1_skb_0
	v_add_u32_e32 v128, 0x10000, v216
	ds_read_b128 v[146:149], v128
	ds_read_b128 v[150:153], v128 offset:1024
	ds_read_b128 v[154:157], v128 offset:2048
	ds_read_b128 v[158:161], v128 offset:3072
.Lpc1_skb_0:
	s_and_b64 vcc, exec, s[94:95]
	s_cbranch_vccz .Lpc1_skb_1
	v_add_u32_e32 v128, 0x14000, v216
	ds_read_b128 v[130:133], v128
	ds_read_b128 v[134:137], v128 offset:1024
	ds_read_b128 v[138:141], v128 offset:2048
	ds_read_b128 v[142:145], v128 offset:3072
.Lpc1_skb_1:
	v_lshl_add_u64 v[206:207], s[30:31], 0, v[202:203]
	s_add_i32 m0, s39, 0xc000
	ds_read_b128 v[186:189], v217
	ds_read_b128 v[190:193], v217 offset:1024
	ds_read_b128 v[178:181], v217 offset:2048
	ds_read_b128 v[182:185], v217 offset:3072
	ds_read_b128 v[170:173], v217 offset:4096
	ds_read_b128 v[174:177], v217 offset:5120
	ds_read_b128 v[162:165], v217 offset:6144
	ds_read_b128 v[166:169], v217 offset:7168
	global_load_lds_dwordx4 v[206:207], off
	v_lshl_add_u64 v[206:207], s[30:31], 0, v[204:205]
	s_add_i32 m0, s39, 0xe000
	v_cndmask_b32_e64 v128, 0, 1, s[52:53]
	global_load_lds_dwordx4 v[206:207], off
	s_waitcnt vmcnt(6)
	s_waitcnt lgkmcnt(0)
	v_cmp_ne_u32_e64 s[44:45], 1, v128
	s_andn2_b64 vcc, exec, s[52:53]
	s_barrier
	s_cbranch_vccnz .LBB0_1283
	s_setprio 1
	s_waitcnt lgkmcnt(0)
	v_mfma_f32_16x16x32_bf16 v[124:127], v[146:149], v[186:189], v[124:127]
	v_mfma_f32_16x16x32_bf16 v[120:123], v[154:157], v[186:189], v[120:123]
	v_mfma_f32_16x16x32_bf16 v[108:111], v[146:149], v[178:181], v[108:111]
	v_mfma_f32_16x16x32_bf16 v[104:107], v[154:157], v[178:181], v[104:107]
	v_mfma_f32_16x16x32_bf16 v[92:95], v[146:149], v[170:173], v[92:95]
	v_mfma_f32_16x16x32_bf16 v[88:91], v[154:157], v[170:173], v[88:91]
	v_mfma_f32_16x16x32_bf16 v[76:79], v[146:149], v[162:165], v[76:79]
	v_mfma_f32_16x16x32_bf16 v[72:75], v[154:157], v[162:165], v[72:75]
	v_mfma_f32_16x16x32_bf16 v[124:127], v[150:153], v[190:193], v[124:127]
	v_mfma_f32_16x16x32_bf16 v[120:123], v[158:161], v[190:193], v[120:123]
	v_mfma_f32_16x16x32_bf16 v[108:111], v[150:153], v[182:185], v[108:111]
	v_mfma_f32_16x16x32_bf16 v[104:107], v[158:161], v[182:185], v[104:107]
	v_mfma_f32_16x16x32_bf16 v[92:95], v[150:153], v[174:177], v[92:95]
	v_mfma_f32_16x16x32_bf16 v[88:91], v[158:161], v[174:177], v[88:91]
	v_mfma_f32_16x16x32_bf16 v[76:79], v[150:153], v[166:169], v[76:79]
	v_mfma_f32_16x16x32_bf16 v[72:75], v[158:161], v[166:169], v[72:75]
	s_setprio 0

.LBB0_1285:
	s_add_u32 s34, s30, 0xfffe0080
	s_addc_u32 s35, s31, -1
	s_cmp_eq_u32 s75, 4
	s_cselect_b32 s37, s41, s35
	s_cselect_b32 s36, s50, s34
	s_cselect_b32 s35, s29, s55
	s_cselect_b32 s34, s51, s54
	s_barrier
	s_and_b64 vcc, exec, s[52:53]
	s_mov_b32 m0, s56
	v_lshl_add_u64 v[206:207], s[34:35], 0, v[198:199]
	s_add_u32 s76, s34, 0x20000
	ds_read_b128 v[186:189], v217 offset:16384
	ds_read_b128 v[190:193], v217 offset:17408
	ds_read_b128 v[178:181], v217 offset:18432
	ds_read_b128 v[182:185], v217 offset:19456
	ds_read_b128 v[170:173], v217 offset:20480
	ds_read_b128 v[174:177], v217 offset:21504
	ds_read_b128 v[162:165], v217 offset:22528
	ds_read_b128 v[166:169], v217 offset:23552
	s_cbranch_vccz .Lpc1_dsk_0
	global_load_lds_dwordx4 v[206:207], off
.Lpc1_dsk_0:
	v_lshl_add_u64 v[208:209], s[34:35], 0, v[194:195]
	s_mov_b32 m0, s57
	s_addc_u32 s77, s35, 0
	s_cbranch_vccz .Lpc1_dsk_1
	global_load_lds_dwordx4 v[208:209], off
.Lpc1_dsk_1:
	s_and_b64 vcc, exec, s[94:95]
	v_lshl_add_u64 v[210:211], s[76:77], 0, v[198:199]
	s_mov_b32 m0, s58
	v_lshl_add_u64 v[212:213], s[36:37], 0, v[196:197]
	s_cbranch_vccz .Lpc1_dsk_2
	global_load_lds_dwordx4 v[210:211], off
.Lpc1_dsk_2:
	v_lshl_add_u64 v[210:211], s[76:77], 0, v[194:195]
	s_mov_b32 m0, s59
	s_nop 0
	s_cbranch_vccz .Lpc1_dsk_3
	global_load_lds_dwordx4 v[210:211], off
.Lpc1_dsk_3:
	s_and_b64 vcc, exec, s[44:45]
	v_lshl_add_u64 v[210:211], s[36:37], 0, v[200:201]
	s_mov_b32 m0, s39
	s_nop 0
	global_load_lds_dwordx4 v[210:211], off
	s_mov_b32 m0, s60
	s_nop 0
	global_load_lds_dwordx4 v[212:213], off
	s_waitcnt vmcnt(6)
	s_waitcnt lgkmcnt(0)
	s_barrier
	s_cbranch_vccnz .LBB0_1287
	s_setprio 1
	s_waitcnt lgkmcnt(0)
	v_mfma_f32_16x16x32_bf16 v[60:63], v[146:149], v[186:189], v[60:63]
	v_mfma_f32_16x16x32_bf16 v[56:59], v[154:157], v[186:189], v[56:59]
	v_mfma_f32_16x16x32_bf16 v[44:47], v[146:149], v[178:181], v[44:47]
	v_mfma_f32_16x16x32_bf16 v[40:43], v[154:157], v[178:181], v[40:43]
	v_mfma_f32_16x16x32_bf16 v[28:31], v[146:149], v[170:173], v[28:31]
	v_mfma_f32_16x16x32_bf16 v[24:27], v[154:157], v[170:173], v[24:27]
	v_mfma_f32_16x16x32_bf16 v[12:15], v[146:149], v[162:165], v[12:15]
	v_mfma_f32_16x16x32_bf16 v[8:11], v[154:157], v[162:165], v[8:11]
	v_mfma_f32_16x16x32_bf16 v[60:63], v[150:153], v[190:193], v[60:63]
	v_mfma_f32_16x16x32_bf16 v[56:59], v[158:161], v[190:193], v[56:59]
	v_mfma_f32_16x16x32_bf16 v[44:47], v[150:153], v[182:185], v[44:47]
	v_mfma_f32_16x16x32_bf16 v[40:43], v[158:161], v[182:185], v[40:43]
	v_mfma_f32_16x16x32_bf16 v[28:31], v[150:153], v[174:177], v[28:31]
	v_mfma_f32_16x16x32_bf16 v[24:27], v[158:161], v[174:177], v[24:27]
	v_mfma_f32_16x16x32_bf16 v[12:15], v[150:153], v[166:169], v[12:15]
	v_mfma_f32_16x16x32_bf16 v[8:11], v[158:161], v[166:169], v[8:11]
	s_setprio 0

.LBB0_1289:
	s_barrier
	s_and_b64 vcc, exec, s[52:53]
	s_cbranch_vccz .Lpc1_skb_2
	v_add_u32_e32 v128, 0x18000, v216
	ds_read_b128 v[146:149], v128
	ds_read_b128 v[150:153], v128 offset:1024
	ds_read_b128 v[154:157], v128 offset:2048
	ds_read_b128 v[158:161], v128 offset:3072
.Lpc1_skb_2:
	s_and_b64 vcc, exec, s[94:95]
	s_cbranch_vccz .Lpc1_skb_3
	v_add_u32_e32 v128, 0x1c000, v216
	ds_read_b128 v[130:133], v128
	ds_read_b128 v[134:137], v128 offset:1024
	ds_read_b128 v[138:141], v128 offset:2048
	ds_read_b128 v[142:145], v128 offset:3072
.Lpc1_skb_3:
	s_add_u32 s36, s36, 0x20000
	s_addc_u32 s37, s37, 0
	s_mov_b32 m0, s61
	v_lshl_add_u64 v[218:219], s[36:37], 0, v[200:201]
	ds_read_b128 v[186:189], v217 offset:32768
	ds_read_b128 v[190:193], v217 offset:33792
	ds_read_b128 v[178:181], v217 offset:34816
	ds_read_b128 v[182:185], v217 offset:35840
	ds_read_b128 v[170:173], v217 offset:36864
	ds_read_b128 v[174:177], v217 offset:37888
	ds_read_b128 v[162:165], v217 offset:38912
	ds_read_b128 v[166:169], v217 offset:39936
	global_load_lds_dwordx4 v[218:219], off
	v_lshl_add_u64 v[218:219], s[36:37], 0, v[196:197]
	s_mov_b32 m0, s62
	s_and_b64 vcc, exec, s[44:45]
	global_load_lds_dwordx4 v[218:219], off
	s_waitcnt vmcnt(6)
	s_waitcnt lgkmcnt(0)
	s_barrier
	s_cbranch_vccnz .LBB0_1291
	s_setprio 1
	s_waitcnt lgkmcnt(0)
	v_mfma_f32_16x16x32_bf16 v[124:127], v[146:149], v[186:189], v[124:127]
	v_mfma_f32_16x16x32_bf16 v[120:123], v[154:157], v[186:189], v[120:123]
	v_mfma_f32_16x16x32_bf16 v[108:111], v[146:149], v[178:181], v[108:111]
	v_mfma_f32_16x16x32_bf16 v[104:107], v[154:157], v[178:181], v[104:107]
	v_mfma_f32_16x16x32_bf16 v[92:95], v[146:149], v[170:173], v[92:95]
	v_mfma_f32_16x16x32_bf16 v[88:91], v[154:157], v[170:173], v[88:91]
	v_mfma_f32_16x16x32_bf16 v[76:79], v[146:149], v[162:165], v[76:79]
	v_mfma_f32_16x16x32_bf16 v[72:75], v[154:157], v[162:165], v[72:75]
	v_mfma_f32_16x16x32_bf16 v[124:127], v[150:153], v[190:193], v[124:127]
	v_mfma_f32_16x16x32_bf16 v[120:123], v[158:161], v[190:193], v[120:123]
	v_mfma_f32_16x16x32_bf16 v[108:111], v[150:153], v[182:185], v[108:111]
	v_mfma_f32_16x16x32_bf16 v[104:107], v[158:161], v[182:185], v[104:107]
	v_mfma_f32_16x16x32_bf16 v[92:95], v[150:153], v[174:177], v[92:95]
	v_mfma_f32_16x16x32_bf16 v[88:91], v[158:161], v[174:177], v[88:91]
	v_mfma_f32_16x16x32_bf16 v[76:79], v[150:153], v[166:169], v[76:79]
	v_mfma_f32_16x16x32_bf16 v[72:75], v[158:161], v[166:169], v[72:75]
	s_setprio 0

.LBB0_1293:
	s_barrier
	s_and_b64 vcc, exec, s[52:53]
	s_mov_b32 m0, s65
	v_lshl_add_u64 v[206:207], v[206:207], 0, s[6:7]
	s_add_u32 s34, s34, 0x20080
	ds_read_b128 v[186:189], v217 offset:49152
	ds_read_b128 v[190:193], v217 offset:50176
	ds_read_b128 v[178:181], v217 offset:51200
	ds_read_b128 v[182:185], v217 offset:52224
	ds_read_b128 v[170:173], v217 offset:53248
	ds_read_b128 v[174:177], v217 offset:54272
	ds_read_b128 v[162:165], v217 offset:55296
	ds_read_b128 v[166:169], v217 offset:56320
	s_cbranch_vccz .Lpc1_dsk_4
	global_load_lds_dwordx4 v[206:207], off
.Lpc1_dsk_4:
	v_lshl_add_u64 v[206:207], v[208:209], 0, s[6:7]
	s_mov_b32 m0, s66
	s_addc_u32 s35, s35, 0
	s_cbranch_vccz .Lpc1_dsk_5
	global_load_lds_dwordx4 v[206:207], off
.Lpc1_dsk_5:
	s_and_b64 vcc, exec, s[94:95]
	v_lshl_add_u64 v[206:207], s[34:35], 0, v[198:199]
	s_mov_b32 m0, s71
	s_nop 0
	s_cbranch_vccz .Lpc1_dsk_6
	global_load_lds_dwordx4 v[206:207], off
.Lpc1_dsk_6:
	v_lshl_add_u64 v[206:207], s[34:35], 0, v[194:195]
	s_mov_b32 m0, s72
	s_nop 0
	s_cbranch_vccz .Lpc1_dsk_7
	global_load_lds_dwordx4 v[206:207], off
.Lpc1_dsk_7:
	s_and_b64 vcc, exec, s[44:45]
	v_lshl_add_u64 v[206:207], v[210:211], 0, s[6:7]
	s_mov_b32 m0, s68
	s_nop 0
	global_load_lds_dwordx4 v[206:207], off
	v_lshl_add_u64 v[206:207], v[212:213], 0, s[6:7]
	s_mov_b32 m0, s70
	s_nop 0
	global_load_lds_dwordx4 v[206:207], off
	s_waitcnt vmcnt(6)
	s_waitcnt lgkmcnt(0)
	s_barrier
	s_cbranch_vccnz .LBB0_1295
	s_setprio 1
	s_waitcnt lgkmcnt(0)
	v_mfma_f32_16x16x32_bf16 v[60:63], v[146:149], v[186:189], v[60:63]
	v_mfma_f32_16x16x32_bf16 v[56:59], v[154:157], v[186:189], v[56:59]
	v_mfma_f32_16x16x32_bf16 v[44:47], v[146:149], v[178:181], v[44:47]
	v_mfma_f32_16x16x32_bf16 v[40:43], v[154:157], v[178:181], v[40:43]
	v_mfma_f32_16x16x32_bf16 v[28:31], v[146:149], v[170:173], v[28:31]
	v_mfma_f32_16x16x32_bf16 v[24:27], v[154:157], v[170:173], v[24:27]
	v_mfma_f32_16x16x32_bf16 v[12:15], v[146:149], v[162:165], v[12:15]
	v_mfma_f32_16x16x32_bf16 v[8:11], v[154:157], v[162:165], v[8:11]
	v_mfma_f32_16x16x32_bf16 v[60:63], v[150:153], v[190:193], v[60:63]
	v_mfma_f32_16x16x32_bf16 v[56:59], v[158:161], v[190:193], v[56:59]
	v_mfma_f32_16x16x32_bf16 v[44:47], v[150:153], v[182:185], v[44:47]
	v_mfma_f32_16x16x32_bf16 v[40:43], v[158:161], v[182:185], v[40:43]
	v_mfma_f32_16x16x32_bf16 v[28:31], v[150:153], v[174:177], v[28:31]
	v_mfma_f32_16x16x32_bf16 v[24:27], v[158:161], v[174:177], v[24:27]
	v_mfma_f32_16x16x32_bf16 v[12:15], v[150:153], v[166:169], v[12:15]
	v_mfma_f32_16x16x32_bf16 v[8:11], v[158:161], v[166:169], v[8:11]
	s_setprio 0
